# head-major operand arrays + LDS-DMA operand staging in the scan
# speedup vs baseline: 1.0172x; 1.0040x over previous
; #define SCAN_BAR() asm volatile("s_waitcnt lgkmcnt(0)\n\ts_barrier" ::: "memory")
; __device__ void scan_phase(LAS unsigned char* lds, const Params& p) {
;     ...
;         const int seq = (item & 7) + 8 * (item >> 5), es = (item >> 3) & 3;
;         const int dir = seq & 1, h = (seq >> 1) & 3, b = seq >> 3;
;         const char* Qx = (const char*)((const bf16_t*)(p.ws + (dir ? WS_QB : WS_QF)) + h * 128);
;         const char* Kx = (const char*)((const bf16_t*)(p.ws + (dir ? WS_KB : WS_KF)) + h * 128);
;         const char* Vx = (const char*)((const bf16_t*)(p.ws + WS_V) + h * 128 + es * 32);
;         const char* Rx = (const char*)(RT + (size_t)dir * NCHUNK * 512 + h * 128);
;         const char* Tx = (const char*)(RT + (size_t)(2 + dir) * NCHUNK * 512 + h * 128);
;         const unsigned qoff0 = (unsigned)((dir ? 63 - (tid >> 4) : (tid >> 4)) * 1024 + (tid & 15) * 16), qstep = dir ? (unsigned)-32768 : 32768u;
;         const unsigned voff = (unsigned)((dir ? 63 - (tid >> 3) : (tid >> 3)) * 1024 + (tid & 7) * 8), roff = (unsigned)(tid & 127) * 4u;
;         f32x4 S[2] = {(f32x4){0.f, 0.f, 0.f, 0.f}, (f32x4){0.f, 0.f, 0.f, 0.f}};
;         float tailp = 0.f;
;         u32x4 k4A[2], k4B[2], k4C[2], k4D[2]; u32x4 q4A[2], q4B[2], q4C[2], q4D[2]; u32x2 v4A, v4B, v4C, v4D; float rvA, tlA, rvB, tlB, rvC, tlC, rvD, tlD;
;     ...
;         SCAN_LOAD(0, k4A, q4A, v4A, rvA, tlA); SCAN_LOAD(1, k4B, q4B, v4B, rvB, tlB); SCAN_LOAD(2, k4C, q4C, v4C, rvC, tlC); SCAN_LOAD(3, k4D, q4D, v4D, rvD, tlD);
;         SCAN_STAGE(0, k4A, q4A, v4A, rvA, tlA); SCAN_LOAD(4, k4A, q4A, v4A, rvA, tlA);
;         SCAN_BAR();
.Lsc5_item:
	s_and_b32 s10, s9, 1
	s_lshr_b32 s3, s9, 1
	s_and_b32 s3, s3, 3
	s_lshr_b32 s4, s9, 5
	s_lshr_b32 s5, s9, 3
	s_and_b32 s5, s5, 3
	s_cmp_eq_u32 s10, 0
	s_cselect_b32 s15, 1, -1
	s_cselect_b32 s64, 0, 3
	s_cselect_b32 s65, -4, 0x43
	s_lshl_b32 s16, s4, 2
	s_add_u32 s16, s16, 0x200
	s_lshl_b32 s17, s4, 6
	s_add_u32 s16, s16, s64
	s_add_i32 s17, s17, s65
	s_lshl_b32 s3, s3, 8
	s_lshl_b32 s5, s5, 6
	s_mul_i32 s4, s3, 34816
	s_cmp_eq_u32 s10, 0
	s_mov_b32 s65, 0x5100000
	s_cselect_b32 s64, s65, 0x7300000
	s_add_u32 s64, s64, s4
	s_add_u32 s18, s70, s64
	s_addc_u32 s19, s71, 0
	s_cmp_eq_u32 s10, 0
	s_mov_b32 s65, 0x9500000
	s_cselect_b32 s64, s65, 0xb700000
	s_add_u32 s64, s64, s4
	s_add_u32 s20, s70, s64
	s_addc_u32 s21, s71, 0
	s_add_u32 s64, s3, s5
	s_add_u32 s65, s4, s5
	s_add_u32 s65, s65, 0xd900000
	s_add_u32 s22, s70, s65
	s_addc_u32 s23, s71, 0
	s_lshl_b32 s65, s10, 25
	s_add_u32 s64, s64, s65
	s_add_u32 s28, s68, s64
	s_addc_u32 s29, s69, 0
	s_mul_i32 s64, s10, 0x110000
	s_lshl_b32 s65, s3, 1
	s_add_u32 s64, s64, s65
	s_add_u32 s64, s64, 0x15b00000
	s_add_u32 s24, s70, s64
	s_addc_u32 s25, s71, 0
	s_add_u32 s26, s24, 0x220000
	s_addc_u32 s27, s25, 0
	s_lshl_b32 s64, s9, 16
	s_add_u32 s64, s64, 0xd00000
	s_add_u32 s30, s70, s64
	s_addc_u32 s31, s71, 0
	s_mul_i32 s5, s10, 63
	s_lshl_b32 s3, s7, 4
	v_add_u32_e32 v1, s3, v58
	v_xor_b32_e32 v1, s5, v1
	v_lshlrev_b32_e32 v1, 10, v1
	s_lshl_b32 s3, s8, 5
	v_lshl_add_u32 v57, v59, 3, v1
	v_add_u32_e32 v57, s3, v57
	v_lshrrev_b32_e32 v1, 4, v0
	v_xor_b32_e32 v93, s5, v1
	v_lshlrev_b32_e32 v93, 8, v93
	v_lshl_add_u32 v53, v94, 4, v93
	v_add_u32_e32 v1, 32, v1
	v_xor_b32_e32 v93, s5, v1
	v_lshlrev_b32_e32 v93, 8, v93
	v_lshl_add_u32 v54, v94, 4, v93
	v_lshrrev_b32_e32 v1, 3, v0
	v_xor_b32_e32 v1, s5, v1
	v_lshlrev_b32_e32 v1, 8, v1
	v_and_b32_e32 v93, 7, v0
	v_lshl_add_u32 v55, v93, 3, v1
	v_mov_b32_e32 v42, 0
	v_mov_b32_e32 v43, 0
	v_mov_b32_e32 v44, 0
	v_mov_b32_e32 v45, 0
	v_mov_b32_e32 v46, 0
	v_mov_b32_e32 v47, 0
	v_mov_b32_e32 v48, 0
	v_mov_b32_e32 v49, 0
	v_mov_b32_e32 v52, 0
	v_mov_b32_e32 v160, 0
	v_mov_b32_e32 v161, 0
	v_mov_b32_e32 v162, 0
	v_mov_b32_e32 v163, 0
	v_mov_b32_e32 v176, 0
	v_mov_b32_e32 v177, 0
	s_mov_b32 s3, 0
	s_cmp_lt_u32 s3, 4
	s_cselect_b32 s4, s16, s17
	s_mul_i32 s5, s3, s15
	s_add_i32 s4, s4, s5
	s_lshl_b32 s5, s4, 14
	s_lshl_b32 s4, s4, 11
	s_add_u32 s44, s22, s5
	s_addc_u32 s45, s23, 0
	s_add_u32 s46, s24, s4
	s_addc_u32 s47, s25, 0
	s_add_u32 s50, s26, s4
	s_addc_u32 s51, s27, 0
	global_load_dwordx2 v[2:3], v55, s[44:45]
	global_load_dword v4, v56, s[46:47]
	global_load_dword v5, v56, s[50:51]
	s_mov_b32 s3, 1
	s_cmp_lt_u32 s3, 4
	s_cselect_b32 s4, s16, s17
	s_mul_i32 s5, s3, s15
	s_add_i32 s4, s4, s5
	s_lshl_b32 s5, s4, 14
	s_lshl_b32 s4, s4, 11
	s_add_u32 s44, s22, s5
	s_addc_u32 s45, s23, 0
	s_add_u32 s46, s24, s4
	s_addc_u32 s47, s25, 0
	s_add_u32 s50, s26, s4
	s_addc_u32 s51, s27, 0
	global_load_dwordx2 v[6:7], v55, s[44:45]
	global_load_dword v8, v56, s[46:47]
	global_load_dword v9, v56, s[50:51]
	s_mov_b32 s3, 0
	s_cmp_lt_u32 s3, 4
	s_cselect_b32 s4, s16, s17
	s_mul_i32 s5, s3, s15
	s_add_i32 s4, s4, s5
	s_lshl_b32 s5, s4, 14
	s_lshl_b32 s4, s4, 11
	s_add_u32 s40, s18, s5
	s_addc_u32 s41, s19, 0
	s_add_u32 s42, s20, s5
	s_addc_u32 s43, s21, 0
	s_add_u32 m0, s12, 0
	s_nop 0
	global_load_lds_dwordx4 v53, s[40:41]
	s_add_u32 m0, s12, 8192
	s_nop 0
	global_load_lds_dwordx4 v54, s[40:41]
	s_add_u32 m0, s12, 16384
	s_nop 0
	global_load_lds_dwordx4 v53, s[42:43]
	s_add_u32 m0, s12, 24576
	s_nop 0
	global_load_lds_dwordx4 v54, s[42:43]
	s_mov_b32 s3, 1
	s_cmp_lt_u32 s3, 4
	s_cselect_b32 s4, s16, s17
	s_mul_i32 s5, s3, s15
	s_add_i32 s4, s4, s5
	s_lshl_b32 s5, s4, 14
	s_lshl_b32 s4, s4, 11
	s_add_u32 s40, s18, s5
	s_addc_u32 s41, s19, 0
	s_add_u32 s42, s20, s5
	s_addc_u32 s43, s21, 0
	s_add_u32 m0, s12, 32768
	s_nop 0
	global_load_lds_dwordx4 v53, s[40:41]
	s_add_u32 m0, s12, 40960
	s_nop 0
	global_load_lds_dwordx4 v54, s[40:41]
	s_add_u32 m0, s12, 49152
	s_nop 0
	global_load_lds_dwordx4 v53, s[42:43]
	s_add_u32 m0, s12, 57344
	s_nop 0
	global_load_lds_dwordx4 v54, s[42:43]
	s_waitcnt vmcnt(0)
	ds_write_b64 v63, v[2:3]
	v_add_f32_e32 v92, v4, v52
	v_mul_f32_e32 v92, 0x3fb8aa3b, v92
	v_exp_f32_e32 v92, v92
	v_mov_b32_e32 v52, v5
	ds_write_b32 v78, v92 offset:0
	ds_write_b64 v64, v[6:7]
	v_add_f32_e32 v92, v8, v52
	v_mul_f32_e32 v92, 0x3fb8aa3b, v92
	v_exp_f32_e32 v92, v92
	v_mov_b32_e32 v52, v9
	ds_write_b32 v78, v92 offset:512
	s_mov_b32 s3, 2
	s_cmp_lt_u32 s3, 4
	s_cselect_b32 s4, s16, s17
	s_mul_i32 s5, s3, s15
	s_add_i32 s4, s4, s5
	s_lshl_b32 s5, s4, 14
	s_lshl_b32 s4, s4, 11
	s_add_u32 s44, s22, s5
	s_addc_u32 s45, s23, 0
	s_add_u32 s46, s24, s4
	s_addc_u32 s47, s25, 0
	s_add_u32 s50, s26, s4
	s_addc_u32 s51, s27, 0
	global_load_dwordx2 v[10:11], v55, s[44:45]
	global_load_dword v12, v56, s[46:47]
	global_load_dword v13, v56, s[50:51]
	global_store_dwordx2 v57, v[176:177], s[30:31]
	s_mov_b32 s3, 2
	s_cmp_lt_u32 s3, 4
	s_cselect_b32 s4, s16, s17
	s_mul_i32 s5, s3, s15
	s_add_i32 s4, s4, s5
	s_lshl_b32 s5, s4, 14
	s_lshl_b32 s4, s4, 11
	s_add_u32 s40, s18, s5
	s_addc_u32 s41, s19, 0
	s_add_u32 s42, s20, s5
	s_addc_u32 s43, s21, 0
	s_add_u32 m0, s12, 65536
	s_nop 0
	global_load_lds_dwordx4 v53, s[40:41]
	s_add_u32 m0, s12, 73728
	s_nop 0
	global_load_lds_dwordx4 v54, s[40:41]
	s_add_u32 m0, s12, 81920
	s_nop 0
	global_load_lds_dwordx4 v53, s[42:43]
	s_add_u32 m0, s12, 90112
	s_nop 0
	global_load_lds_dwordx4 v54, s[42:43]
	s_mov_b32 s3, 3
	s_cmp_lt_u32 s3, 4
	s_cselect_b32 s4, s16, s17
	s_mul_i32 s5, s3, s15
	s_add_i32 s4, s4, s5
	s_lshl_b32 s5, s4, 14
	s_lshl_b32 s4, s4, 11
	s_add_u32 s44, s22, s5
	s_addc_u32 s45, s23, 0
	s_add_u32 s46, s24, s4
	s_addc_u32 s47, s25, 0
	s_add_u32 s50, s26, s4
	s_addc_u32 s51, s27, 0
	global_load_dwordx2 v[2:3], v55, s[44:45]
	global_load_dword v4, v56, s[46:47]
	global_load_dword v5, v56, s[50:51]
	global_store_dwordx2 v57, v[176:177], s[30:31]
	s_waitcnt lgkmcnt(0)
	s_barrier
	ds_read_b32 v50, v79 offset:0
	ds_read_b32 v51, v79 offset:64
	ds_read_b128 v[96:99], v14
	ds_read_b128 v[100:103], v15
	ds_read_b128 v[104:107], v16
	ds_read_b128 v[108:111], v17
	ds_read_b128 v[216:219], v26
	ds_read_b128 v[220:223], v27
	ds_read_b128 v[224:227], v28
	ds_read_b128 v[228:231], v29
	s_waitcnt lgkmcnt(0)
	ds_read_b64_tr_b16 v[136:137], v38 offset:0
	ds_read_b64_tr_b16 v[138:139], v38 offset:4096
	ds_read_b64_tr_b16 v[140:141], v39 offset:0
	ds_read_b64_tr_b16 v[142:143], v39 offset:4096
	ds_read_b64_tr_b16 v[144:145], v38 offset:8192
	ds_read_b64_tr_b16 v[146:147], v38 offset:12288
	ds_read_b64_tr_b16 v[148:149], v39 offset:8192
	ds_read_b64_tr_b16 v[150:151], v39 offset:12288
	s_cmp_eq_u32 s14, 0
	s_cbranch_scc1 .Lsc5_noy_p
	ds_read_b128 v[232:235], v26 offset:8192
	ds_read_b128 v[236:239], v27 offset:8192
	ds_read_b128 v[240:243], v28 offset:8192
	ds_read_b128 v[244:247], v29 offset:8192

.Lsc5_loop:
	ds_read_b32 v50, v79 offset:512
	ds_read_b32 v51, v79 offset:576
	ds_read_b64_tr_b16 v[128:129], v72 offset:0
	ds_read_b64_tr_b16 v[130:131], v72 offset:1152
	ds_read_b64_tr_b16 v[132:133], v72 offset:2304
	ds_read_b64_tr_b16 v[134:135], v72 offset:3456
	ds_read_b64_tr_b16 v[112:113], v82 offset:0
	ds_read_b64_tr_b16 v[114:115], v82 offset:288
	ds_read_b64_tr_b16 v[116:117], v82 offset:2304
	ds_read_b64_tr_b16 v[118:119], v82 offset:2592
	ds_read_b64_tr_b16 v[120:121], v82 offset:4608
	ds_read_b64_tr_b16 v[122:123], v82 offset:4896
	ds_read_b64_tr_b16 v[124:125], v82 offset:6912
	ds_read_b64_tr_b16 v[126:127], v82 offset:7200
	s_add_u32 s3, s34, 3
	s_min_u32 s3, s3, 67
	s_cmp_lt_u32 s3, 4
	s_cselect_b32 s4, s16, s17
	s_mul_i32 s5, s3, s15
	s_add_i32 s4, s4, s5
	s_lshl_b32 s5, s4, 14
	s_lshl_b32 s4, s4, 11
	s_add_u32 s40, s18, s5
	s_addc_u32 s41, s19, 0
	s_add_u32 s42, s20, s5
	s_addc_u32 s43, s21, 0
	s_add_u32 m0, s12, 0
	s_nop 0
	global_load_lds_dwordx4 v53, s[40:41]
	s_add_u32 m0, s12, 8192
	s_nop 0
	global_load_lds_dwordx4 v54, s[40:41]
	s_add_u32 m0, s12, 16384
	s_nop 0
	global_load_lds_dwordx4 v53, s[42:43]
	s_add_u32 m0, s12, 24576
	s_nop 0
	global_load_lds_dwordx4 v54, s[42:43]
	s_add_u32 s3, s34, 4
	s_min_u32 s3, s3, 67
	s_cmp_lt_u32 s3, 4
	s_cselect_b32 s4, s16, s17
	s_mul_i32 s5, s3, s15
	s_add_i32 s4, s4, s5
	s_lshl_b32 s5, s4, 14
	s_lshl_b32 s4, s4, 11
	s_add_u32 s44, s22, s5
	s_addc_u32 s45, s23, 0
	s_add_u32 s46, s24, s4
	s_addc_u32 s47, s25, 0
	s_add_u32 s50, s26, s4
	s_addc_u32 s51, s27, 0
	global_load_dwordx2 v[6:7], v55, s[44:45]
	global_load_dword v8, v56, s[46:47]
	global_load_dword v9, v56, s[50:51]
	s_waitcnt lgkmcnt(8)
	v_mfma_f32_16x16x32_bf16 v[42:45], v[128:131], v[136:139], v[42:45]
	ds_read_b128 v[164:167], v86
	ds_read_b128 v[168:171], v86 offset:1024
	v_mfma_f32_16x16x32_bf16 v[46:49], v[128:131], v[140:143], v[46:49]
	ds_read_b128 v[200:203], v18
	ds_read_b128 v[204:207], v19
	v_mfma_f32_16x16x32_bf16 v[42:45], v[132:135], v[144:147], v[42:45]
	ds_read_b128 v[208:211], v20
	ds_read_b128 v[212:215], v21
	v_mfma_f32_16x16x32_bf16 v[46:49], v[132:135], v[148:151], v[46:49]
	s_waitcnt lgkmcnt(12)
	v_mfma_f32_16x16x32_bf16 v[172:175], v[112:115], v[96:99], 0
	s_waitcnt vmcnt(16)
	ds_write_b64 v65, v[10:11]
	v_add_f32_e32 v92, v12, v52
	v_mul_f32_e32 v92, 0x3fb8aa3b, v92
	v_exp_f32_e32 v92, v92
	v_mov_b32_e32 v52, v13
	ds_write_b32 v78, v92 offset:1024
	s_waitcnt lgkmcnt(12)
	v_mfma_f32_16x16x32_bf16 v[172:175], v[116:119], v[100:103], v[172:175]
	ds_read_b128 v[216:219], v30
	ds_read_b128 v[220:223], v31
	s_waitcnt lgkmcnt(12)
	v_mfma_f32_16x16x32_bf16 v[172:175], v[120:123], v[104:107], v[172:175]
	ds_read_b128 v[224:227], v32
	ds_read_b128 v[228:231], v33
	s_waitcnt lgkmcnt(12)
	v_mfma_f32_16x16x32_bf16 v[172:175], v[124:127], v[108:111], v[172:175]
	ds_read_b64_tr_b16 v[188:189], v40 offset:0
	ds_read_b64_tr_b16 v[190:191], v40 offset:4096
	s_waitcnt lgkmcnt(13)
	v_mfma_f32_16x16x32_bf16 v[172:175], v[128:131], v[164:167], v[172:175]
	ds_read_b64_tr_b16 v[192:193], v41 offset:0
	ds_read_b64_tr_b16 v[194:195], v41 offset:4096
	s_waitcnt lgkmcnt(14)
	s_cmp_eq_u32 s11, 0
	s_cbranch_scc1 .Lsc5_nopv1_0
	v_mfma_f32_16x16x32_bf16 v[172:175], v[132:135], v[168:171], v[172:175]

.Lsc5_noy3_0:
	ds_write_b64 v85, v[160:161]
	ds_write_b64 v85, v[162:163] offset:1024
	s_waitcnt vmcnt(12)
	s_waitcnt lgkmcnt(0)
	s_barrier
	ds_read_b32 v50, v79 offset:1024
	ds_read_b32 v51, v79 offset:1088
	ds_read_b64_tr_b16 v[128:129], v73 offset:0
	ds_read_b64_tr_b16 v[130:131], v73 offset:1152
	ds_read_b64_tr_b16 v[132:133], v73 offset:2304
	ds_read_b64_tr_b16 v[134:135], v73 offset:3456
	ds_read_b64_tr_b16 v[112:113], v83 offset:0
	ds_read_b64_tr_b16 v[114:115], v83 offset:288
	ds_read_b64_tr_b16 v[116:117], v83 offset:2304
	ds_read_b64_tr_b16 v[118:119], v83 offset:2592
	ds_read_b64_tr_b16 v[120:121], v83 offset:4608
	ds_read_b64_tr_b16 v[122:123], v83 offset:4896
	ds_read_b64_tr_b16 v[124:125], v83 offset:6912
	ds_read_b64_tr_b16 v[126:127], v83 offset:7200
	s_add_u32 s3, s34, 4
	s_min_u32 s3, s3, 67
	s_cmp_lt_u32 s3, 4
	s_cselect_b32 s4, s16, s17
	s_mul_i32 s5, s3, s15
	s_add_i32 s4, s4, s5
	s_lshl_b32 s5, s4, 14
	s_lshl_b32 s4, s4, 11
	s_add_u32 s40, s18, s5
	s_addc_u32 s41, s19, 0
	s_add_u32 s42, s20, s5
	s_addc_u32 s43, s21, 0
	s_add_u32 m0, s12, 32768
	s_nop 0
	global_load_lds_dwordx4 v53, s[40:41]
	s_add_u32 m0, s12, 40960
	s_nop 0
	global_load_lds_dwordx4 v54, s[40:41]
	s_add_u32 m0, s12, 49152
	s_nop 0
	global_load_lds_dwordx4 v53, s[42:43]
	s_add_u32 m0, s12, 57344
	s_nop 0
	global_load_lds_dwordx4 v54, s[42:43]
	s_add_u32 s3, s34, 5
	s_min_u32 s3, s3, 67
	s_cmp_lt_u32 s3, 4
	s_cselect_b32 s4, s16, s17
	s_mul_i32 s5, s3, s15
	s_add_i32 s4, s4, s5
	s_lshl_b32 s5, s4, 14
	s_lshl_b32 s4, s4, 11
	s_add_u32 s44, s22, s5
	s_addc_u32 s45, s23, 0
	s_add_u32 s46, s24, s4
	s_addc_u32 s47, s25, 0
	s_add_u32 s50, s26, s4
	s_addc_u32 s51, s27, 0
	global_load_dwordx2 v[10:11], v55, s[44:45]
	global_load_dword v12, v56, s[46:47]
	global_load_dword v13, v56, s[50:51]
	s_waitcnt lgkmcnt(8)
	v_mfma_f32_16x16x32_bf16 v[42:45], v[128:131], v[188:191], v[42:45]
	ds_read_b128 v[164:167], v87
	ds_read_b128 v[168:171], v87 offset:1024
	v_mfma_f32_16x16x32_bf16 v[46:49], v[128:131], v[192:195], v[46:49]
	ds_read_b128 v[96:99], v22
	ds_read_b128 v[100:103], v23
	v_mfma_f32_16x16x32_bf16 v[42:45], v[132:135], v[196:199], v[42:45]
	ds_read_b128 v[104:107], v24
	ds_read_b128 v[108:111], v25
	v_mfma_f32_16x16x32_bf16 v[46:49], v[132:135], v[248:251], v[46:49]
	s_waitcnt lgkmcnt(12)
	v_mfma_f32_16x16x32_bf16 v[172:175], v[112:115], v[200:203], 0
	s_waitcnt vmcnt(16)
	ds_write_b64 v63, v[2:3]
	v_add_f32_e32 v92, v4, v52
	v_mul_f32_e32 v92, 0x3fb8aa3b, v92
	v_exp_f32_e32 v92, v92
	v_mov_b32_e32 v52, v5
	ds_write_b32 v78, v92 offset:0
	s_waitcnt lgkmcnt(12)
	v_mfma_f32_16x16x32_bf16 v[172:175], v[116:119], v[204:207], v[172:175]
	ds_read_b128 v[216:219], v34
	ds_read_b128 v[220:223], v35
	s_waitcnt lgkmcnt(12)
	v_mfma_f32_16x16x32_bf16 v[172:175], v[120:123], v[208:211], v[172:175]
	ds_read_b128 v[224:227], v36
	ds_read_b128 v[228:231], v37
	s_waitcnt lgkmcnt(12)
	v_mfma_f32_16x16x32_bf16 v[172:175], v[124:127], v[212:215], v[172:175]
	ds_read_b64_tr_b16 v[136:137], v180 offset:0
	ds_read_b64_tr_b16 v[138:139], v180 offset:4096
	s_waitcnt lgkmcnt(13)
	v_mfma_f32_16x16x32_bf16 v[172:175], v[128:131], v[164:167], v[172:175]
	ds_read_b64_tr_b16 v[140:141], v181 offset:0
	ds_read_b64_tr_b16 v[142:143], v181 offset:4096
	s_waitcnt lgkmcnt(14)
	s_cmp_eq_u32 s11, 0
	s_cbranch_scc1 .Lsc5_nopv1_1
	v_mfma_f32_16x16x32_bf16 v[172:175], v[132:135], v[168:171], v[172:175]

.Lsc5_noy3_1:
	ds_write_b64 v84, v[160:161]
	ds_write_b64 v84, v[162:163] offset:1024
	s_waitcnt vmcnt(12)
	s_waitcnt lgkmcnt(0)
	s_barrier
	ds_read_b32 v50, v79 offset:0
	ds_read_b32 v51, v79 offset:64
	ds_read_b64_tr_b16 v[128:129], v74 offset:0
	ds_read_b64_tr_b16 v[130:131], v74 offset:1152
	ds_read_b64_tr_b16 v[132:133], v74 offset:2304
	ds_read_b64_tr_b16 v[134:135], v74 offset:3456
	ds_read_b64_tr_b16 v[112:113], v82 offset:0
	ds_read_b64_tr_b16 v[114:115], v82 offset:288
	ds_read_b64_tr_b16 v[116:117], v82 offset:2304
	ds_read_b64_tr_b16 v[118:119], v82 offset:2592
	ds_read_b64_tr_b16 v[120:121], v82 offset:4608
	ds_read_b64_tr_b16 v[122:123], v82 offset:4896
	ds_read_b64_tr_b16 v[124:125], v82 offset:6912
	ds_read_b64_tr_b16 v[126:127], v82 offset:7200
	s_add_u32 s3, s34, 5
	s_min_u32 s3, s3, 67
	s_cmp_lt_u32 s3, 4
	s_cselect_b32 s4, s16, s17
	s_mul_i32 s5, s3, s15
	s_add_i32 s4, s4, s5
	s_lshl_b32 s5, s4, 14
	s_lshl_b32 s4, s4, 11
	s_add_u32 s40, s18, s5
	s_addc_u32 s41, s19, 0
	s_add_u32 s42, s20, s5
	s_addc_u32 s43, s21, 0
	s_add_u32 m0, s12, 65536
	s_nop 0
	global_load_lds_dwordx4 v53, s[40:41]
	s_add_u32 m0, s12, 73728
	s_nop 0
	global_load_lds_dwordx4 v54, s[40:41]
	s_add_u32 m0, s12, 81920
	s_nop 0
	global_load_lds_dwordx4 v53, s[42:43]
	s_add_u32 m0, s12, 90112
	s_nop 0
	global_load_lds_dwordx4 v54, s[42:43]
	s_add_u32 s3, s34, 6
	s_min_u32 s3, s3, 67
	s_cmp_lt_u32 s3, 4
	s_cselect_b32 s4, s16, s17
	s_mul_i32 s5, s3, s15
	s_add_i32 s4, s4, s5
	s_lshl_b32 s5, s4, 14
	s_lshl_b32 s4, s4, 11
	s_add_u32 s44, s22, s5
	s_addc_u32 s45, s23, 0
	s_add_u32 s46, s24, s4
	s_addc_u32 s47, s25, 0
	s_add_u32 s50, s26, s4
	s_addc_u32 s51, s27, 0
	global_load_dwordx2 v[2:3], v55, s[44:45]
	global_load_dword v4, v56, s[46:47]
	global_load_dword v5, v56, s[50:51]
	s_waitcnt lgkmcnt(8)
	v_mfma_f32_16x16x32_bf16 v[42:45], v[128:131], v[136:139], v[42:45]
	ds_read_b128 v[164:167], v86
	ds_read_b128 v[168:171], v86 offset:1024
	v_mfma_f32_16x16x32_bf16 v[46:49], v[128:131], v[140:143], v[46:49]
	ds_read_b128 v[200:203], v14
	ds_read_b128 v[204:207], v15
	v_mfma_f32_16x16x32_bf16 v[42:45], v[132:135], v[144:147], v[42:45]
	ds_read_b128 v[208:211], v16
	ds_read_b128 v[212:215], v17
	v_mfma_f32_16x16x32_bf16 v[46:49], v[132:135], v[148:151], v[46:49]
	s_waitcnt lgkmcnt(12)
	v_mfma_f32_16x16x32_bf16 v[172:175], v[112:115], v[96:99], 0
	s_waitcnt vmcnt(16)
	ds_write_b64 v64, v[6:7]
	v_add_f32_e32 v92, v8, v52
	v_mul_f32_e32 v92, 0x3fb8aa3b, v92
	v_exp_f32_e32 v92, v92
	v_mov_b32_e32 v52, v9
	ds_write_b32 v78, v92 offset:512
	s_waitcnt lgkmcnt(12)
	v_mfma_f32_16x16x32_bf16 v[172:175], v[116:119], v[100:103], v[172:175]
	ds_read_b128 v[216:219], v26
	ds_read_b128 v[220:223], v27
	s_waitcnt lgkmcnt(12)
	v_mfma_f32_16x16x32_bf16 v[172:175], v[120:123], v[104:107], v[172:175]
	ds_read_b128 v[224:227], v28
	ds_read_b128 v[228:231], v29
	s_waitcnt lgkmcnt(12)
	v_mfma_f32_16x16x32_bf16 v[172:175], v[124:127], v[108:111], v[172:175]
	ds_read_b64_tr_b16 v[188:189], v38 offset:0
	ds_read_b64_tr_b16 v[190:191], v38 offset:4096
	s_waitcnt lgkmcnt(13)
	v_mfma_f32_16x16x32_bf16 v[172:175], v[128:131], v[164:167], v[172:175]
	ds_read_b64_tr_b16 v[192:193], v39 offset:0
	ds_read_b64_tr_b16 v[194:195], v39 offset:4096
	s_waitcnt lgkmcnt(14)
	s_cmp_eq_u32 s11, 0
	s_cbranch_scc1 .Lsc5_nopv1_2
	v_mfma_f32_16x16x32_bf16 v[172:175], v[132:135], v[168:171], v[172:175]

.Lsc5_noy3_2:
	ds_write_b64 v85, v[160:161]
	ds_write_b64 v85, v[162:163] offset:1024
	s_waitcnt vmcnt(12)
	s_waitcnt lgkmcnt(0)
	s_barrier
	ds_read_b32 v50, v79 offset:512
	ds_read_b32 v51, v79 offset:576
	ds_read_b64_tr_b16 v[128:129], v72 offset:0
	ds_read_b64_tr_b16 v[130:131], v72 offset:1152
	ds_read_b64_tr_b16 v[132:133], v72 offset:2304
	ds_read_b64_tr_b16 v[134:135], v72 offset:3456
	ds_read_b64_tr_b16 v[112:113], v83 offset:0
	ds_read_b64_tr_b16 v[114:115], v83 offset:288
	ds_read_b64_tr_b16 v[116:117], v83 offset:2304
	ds_read_b64_tr_b16 v[118:119], v83 offset:2592
	ds_read_b64_tr_b16 v[120:121], v83 offset:4608
	ds_read_b64_tr_b16 v[122:123], v83 offset:4896
	ds_read_b64_tr_b16 v[124:125], v83 offset:6912
	ds_read_b64_tr_b16 v[126:127], v83 offset:7200
	s_add_u32 s3, s34, 6
	s_min_u32 s3, s3, 67
	s_cmp_lt_u32 s3, 4
	s_cselect_b32 s4, s16, s17
	s_mul_i32 s5, s3, s15
	s_add_i32 s4, s4, s5
	s_lshl_b32 s5, s4, 14
	s_lshl_b32 s4, s4, 11
	s_add_u32 s40, s18, s5
	s_addc_u32 s41, s19, 0
	s_add_u32 s42, s20, s5
	s_addc_u32 s43, s21, 0
	s_add_u32 m0, s12, 0
	s_nop 0
	global_load_lds_dwordx4 v53, s[40:41]
	s_add_u32 m0, s12, 8192
	s_nop 0
	global_load_lds_dwordx4 v54, s[40:41]
	s_add_u32 m0, s12, 16384
	s_nop 0
	global_load_lds_dwordx4 v53, s[42:43]
	s_add_u32 m0, s12, 24576
	s_nop 0
	global_load_lds_dwordx4 v54, s[42:43]
	s_add_u32 s3, s34, 7
	s_min_u32 s3, s3, 67
	s_cmp_lt_u32 s3, 4
	s_cselect_b32 s4, s16, s17
	s_mul_i32 s5, s3, s15
	s_add_i32 s4, s4, s5
	s_lshl_b32 s5, s4, 14
	s_lshl_b32 s4, s4, 11
	s_add_u32 s44, s22, s5
	s_addc_u32 s45, s23, 0
	s_add_u32 s46, s24, s4
	s_addc_u32 s47, s25, 0
	s_add_u32 s50, s26, s4
	s_addc_u32 s51, s27, 0
	global_load_dwordx2 v[6:7], v55, s[44:45]
	global_load_dword v8, v56, s[46:47]
	global_load_dword v9, v56, s[50:51]
	s_waitcnt lgkmcnt(8)
	v_mfma_f32_16x16x32_bf16 v[42:45], v[128:131], v[188:191], v[42:45]
	ds_read_b128 v[164:167], v87
	ds_read_b128 v[168:171], v87 offset:1024
	v_mfma_f32_16x16x32_bf16 v[46:49], v[128:131], v[192:195], v[46:49]
	ds_read_b128 v[96:99], v18
	ds_read_b128 v[100:103], v19
	v_mfma_f32_16x16x32_bf16 v[42:45], v[132:135], v[196:199], v[42:45]
	ds_read_b128 v[104:107], v20
	ds_read_b128 v[108:111], v21
	v_mfma_f32_16x16x32_bf16 v[46:49], v[132:135], v[248:251], v[46:49]
	s_waitcnt lgkmcnt(12)
	v_mfma_f32_16x16x32_bf16 v[172:175], v[112:115], v[200:203], 0
	s_waitcnt vmcnt(16)
	ds_write_b64 v65, v[10:11]
	v_add_f32_e32 v92, v12, v52
	v_mul_f32_e32 v92, 0x3fb8aa3b, v92
	v_exp_f32_e32 v92, v92
	v_mov_b32_e32 v52, v13
	ds_write_b32 v78, v92 offset:1024
	s_waitcnt lgkmcnt(12)
	v_mfma_f32_16x16x32_bf16 v[172:175], v[116:119], v[204:207], v[172:175]
	ds_read_b128 v[216:219], v30
	ds_read_b128 v[220:223], v31
	s_waitcnt lgkmcnt(12)
	v_mfma_f32_16x16x32_bf16 v[172:175], v[120:123], v[208:211], v[172:175]
	ds_read_b128 v[224:227], v32
	ds_read_b128 v[228:231], v33
	s_waitcnt lgkmcnt(12)
	v_mfma_f32_16x16x32_bf16 v[172:175], v[124:127], v[212:215], v[172:175]
	ds_read_b64_tr_b16 v[136:137], v40 offset:0
	ds_read_b64_tr_b16 v[138:139], v40 offset:4096
	s_waitcnt lgkmcnt(13)
	v_mfma_f32_16x16x32_bf16 v[172:175], v[128:131], v[164:167], v[172:175]
	ds_read_b64_tr_b16 v[140:141], v41 offset:0
	ds_read_b64_tr_b16 v[142:143], v41 offset:4096
	s_waitcnt lgkmcnt(14)
	s_cmp_eq_u32 s11, 0
	s_cbranch_scc1 .Lsc5_nopv1_3
	v_mfma_f32_16x16x32_bf16 v[172:175], v[132:135], v[168:171], v[172:175]

.Lsc5_noy3_3:
	ds_write_b64 v84, v[160:161]
	ds_write_b64 v84, v[162:163] offset:1024
	s_waitcnt vmcnt(12)
	s_waitcnt lgkmcnt(0)
	s_barrier
	ds_read_b32 v50, v79 offset:1024
	ds_read_b32 v51, v79 offset:1088
	ds_read_b64_tr_b16 v[128:129], v73 offset:0
	ds_read_b64_tr_b16 v[130:131], v73 offset:1152
	ds_read_b64_tr_b16 v[132:133], v73 offset:2304
	ds_read_b64_tr_b16 v[134:135], v73 offset:3456
	ds_read_b64_tr_b16 v[112:113], v82 offset:0
	ds_read_b64_tr_b16 v[114:115], v82 offset:288
	ds_read_b64_tr_b16 v[116:117], v82 offset:2304
	ds_read_b64_tr_b16 v[118:119], v82 offset:2592
	ds_read_b64_tr_b16 v[120:121], v82 offset:4608
	ds_read_b64_tr_b16 v[122:123], v82 offset:4896
	ds_read_b64_tr_b16 v[124:125], v82 offset:6912
	ds_read_b64_tr_b16 v[126:127], v82 offset:7200
	s_add_u32 s3, s34, 7
	s_min_u32 s3, s3, 67
	s_cmp_lt_u32 s3, 4
	s_cselect_b32 s4, s16, s17
	s_mul_i32 s5, s3, s15
	s_add_i32 s4, s4, s5
	s_lshl_b32 s5, s4, 14
	s_lshl_b32 s4, s4, 11
	s_add_u32 s40, s18, s5
	s_addc_u32 s41, s19, 0
	s_add_u32 s42, s20, s5
	s_addc_u32 s43, s21, 0
	s_add_u32 m0, s12, 32768
	s_nop 0
	global_load_lds_dwordx4 v53, s[40:41]
	s_add_u32 m0, s12, 40960
	s_nop 0
	global_load_lds_dwordx4 v54, s[40:41]
	s_add_u32 m0, s12, 49152
	s_nop 0
	global_load_lds_dwordx4 v53, s[42:43]
	s_add_u32 m0, s12, 57344
	s_nop 0
	global_load_lds_dwordx4 v54, s[42:43]
	s_add_u32 s3, s34, 8
	s_min_u32 s3, s3, 67
	s_cmp_lt_u32 s3, 4
	s_cselect_b32 s4, s16, s17
	s_mul_i32 s5, s3, s15
	s_add_i32 s4, s4, s5
	s_lshl_b32 s5, s4, 14
	s_lshl_b32 s4, s4, 11
	s_add_u32 s44, s22, s5
	s_addc_u32 s45, s23, 0
	s_add_u32 s46, s24, s4
	s_addc_u32 s47, s25, 0
	s_add_u32 s50, s26, s4
	s_addc_u32 s51, s27, 0
	global_load_dwordx2 v[10:11], v55, s[44:45]
	global_load_dword v12, v56, s[46:47]
	global_load_dword v13, v56, s[50:51]
	s_waitcnt lgkmcnt(8)
	v_mfma_f32_16x16x32_bf16 v[42:45], v[128:131], v[136:139], v[42:45]
	ds_read_b128 v[164:167], v86
	ds_read_b128 v[168:171], v86 offset:1024
	v_mfma_f32_16x16x32_bf16 v[46:49], v[128:131], v[140:143], v[46:49]
	ds_read_b128 v[200:203], v22
	ds_read_b128 v[204:207], v23
	v_mfma_f32_16x16x32_bf16 v[42:45], v[132:135], v[144:147], v[42:45]
	ds_read_b128 v[208:211], v24
	ds_read_b128 v[212:215], v25
	v_mfma_f32_16x16x32_bf16 v[46:49], v[132:135], v[148:151], v[46:49]
	s_waitcnt lgkmcnt(12)
	v_mfma_f32_16x16x32_bf16 v[172:175], v[112:115], v[96:99], 0
	s_waitcnt vmcnt(16)
	ds_write_b64 v63, v[2:3]
	v_add_f32_e32 v92, v4, v52
	v_mul_f32_e32 v92, 0x3fb8aa3b, v92
	v_exp_f32_e32 v92, v92
	v_mov_b32_e32 v52, v5
	ds_write_b32 v78, v92 offset:0
	s_waitcnt lgkmcnt(12)
	v_mfma_f32_16x16x32_bf16 v[172:175], v[116:119], v[100:103], v[172:175]
	ds_read_b128 v[216:219], v34
	ds_read_b128 v[220:223], v35
	s_waitcnt lgkmcnt(12)
	v_mfma_f32_16x16x32_bf16 v[172:175], v[120:123], v[104:107], v[172:175]
	ds_read_b128 v[224:227], v36
	ds_read_b128 v[228:231], v37
	s_waitcnt lgkmcnt(12)
	v_mfma_f32_16x16x32_bf16 v[172:175], v[124:127], v[108:111], v[172:175]
	ds_read_b64_tr_b16 v[188:189], v180 offset:0
	ds_read_b64_tr_b16 v[190:191], v180 offset:4096
	s_waitcnt lgkmcnt(13)
	v_mfma_f32_16x16x32_bf16 v[172:175], v[128:131], v[164:167], v[172:175]
	ds_read_b64_tr_b16 v[192:193], v181 offset:0
	ds_read_b64_tr_b16 v[194:195], v181 offset:4096
	s_waitcnt lgkmcnt(14)
	s_cmp_eq_u32 s11, 0
	s_cbranch_scc1 .Lsc5_nopv1_4
	v_mfma_f32_16x16x32_bf16 v[172:175], v[132:135], v[168:171], v[172:175]

.Lsc5_noy3_4:
	ds_write_b64 v85, v[160:161]
	ds_write_b64 v85, v[162:163] offset:1024
	s_waitcnt vmcnt(12)
	s_waitcnt lgkmcnt(0)
	s_barrier
	ds_read_b32 v50, v79 offset:0
	ds_read_b32 v51, v79 offset:64
	ds_read_b64_tr_b16 v[128:129], v74 offset:0
	ds_read_b64_tr_b16 v[130:131], v74 offset:1152
	ds_read_b64_tr_b16 v[132:133], v74 offset:2304
	ds_read_b64_tr_b16 v[134:135], v74 offset:3456
	ds_read_b64_tr_b16 v[112:113], v83 offset:0
	ds_read_b64_tr_b16 v[114:115], v83 offset:288
	ds_read_b64_tr_b16 v[116:117], v83 offset:2304
	ds_read_b64_tr_b16 v[118:119], v83 offset:2592
	ds_read_b64_tr_b16 v[120:121], v83 offset:4608
	ds_read_b64_tr_b16 v[122:123], v83 offset:4896
	ds_read_b64_tr_b16 v[124:125], v83 offset:6912
	ds_read_b64_tr_b16 v[126:127], v83 offset:7200
	s_add_u32 s3, s34, 8
	s_min_u32 s3, s3, 67
	s_cmp_lt_u32 s3, 4
	s_cselect_b32 s4, s16, s17
	s_mul_i32 s5, s3, s15
	s_add_i32 s4, s4, s5
	s_lshl_b32 s5, s4, 14
	s_lshl_b32 s4, s4, 11
	s_add_u32 s40, s18, s5
	s_addc_u32 s41, s19, 0
	s_add_u32 s42, s20, s5
	s_addc_u32 s43, s21, 0
	s_add_u32 m0, s12, 65536
	s_nop 0
	global_load_lds_dwordx4 v53, s[40:41]
	s_add_u32 m0, s12, 73728
	s_nop 0
	global_load_lds_dwordx4 v54, s[40:41]
	s_add_u32 m0, s12, 81920
	s_nop 0
	global_load_lds_dwordx4 v53, s[42:43]
	s_add_u32 m0, s12, 90112
	s_nop 0
	global_load_lds_dwordx4 v54, s[42:43]
	s_add_u32 s3, s34, 9
	s_min_u32 s3, s3, 67
	s_cmp_lt_u32 s3, 4
	s_cselect_b32 s4, s16, s17
	s_mul_i32 s5, s3, s15
	s_add_i32 s4, s4, s5
	s_lshl_b32 s5, s4, 14
	s_lshl_b32 s4, s4, 11
	s_add_u32 s44, s22, s5
	s_addc_u32 s45, s23, 0
	s_add_u32 s46, s24, s4
	s_addc_u32 s47, s25, 0
	s_add_u32 s50, s26, s4
	s_addc_u32 s51, s27, 0
	global_load_dwordx2 v[2:3], v55, s[44:45]
	global_load_dword v4, v56, s[46:47]
	global_load_dword v5, v56, s[50:51]
	s_waitcnt lgkmcnt(8)
	v_mfma_f32_16x16x32_bf16 v[42:45], v[128:131], v[188:191], v[42:45]
	ds_read_b128 v[164:167], v87
	ds_read_b128 v[168:171], v87 offset:1024
	v_mfma_f32_16x16x32_bf16 v[46:49], v[128:131], v[192:195], v[46:49]
	ds_read_b128 v[96:99], v14
	ds_read_b128 v[100:103], v15
	v_mfma_f32_16x16x32_bf16 v[42:45], v[132:135], v[196:199], v[42:45]
	ds_read_b128 v[104:107], v16
	ds_read_b128 v[108:111], v17
	v_mfma_f32_16x16x32_bf16 v[46:49], v[132:135], v[248:251], v[46:49]
	s_waitcnt lgkmcnt(12)
	v_mfma_f32_16x16x32_bf16 v[172:175], v[112:115], v[200:203], 0
	s_waitcnt vmcnt(16)
	ds_write_b64 v64, v[6:7]
	v_add_f32_e32 v92, v8, v52
	v_mul_f32_e32 v92, 0x3fb8aa3b, v92
	v_exp_f32_e32 v92, v92
	v_mov_b32_e32 v52, v9
	ds_write_b32 v78, v92 offset:512
	s_waitcnt lgkmcnt(12)
	v_mfma_f32_16x16x32_bf16 v[172:175], v[116:119], v[204:207], v[172:175]
	ds_read_b128 v[216:219], v26
	ds_read_b128 v[220:223], v27
	s_waitcnt lgkmcnt(12)
	v_mfma_f32_16x16x32_bf16 v[172:175], v[120:123], v[208:211], v[172:175]
	ds_read_b128 v[224:227], v28
	ds_read_b128 v[228:231], v29
	s_waitcnt lgkmcnt(12)
	v_mfma_f32_16x16x32_bf16 v[172:175], v[124:127], v[212:215], v[172:175]
	ds_read_b64_tr_b16 v[136:137], v38 offset:0
	ds_read_b64_tr_b16 v[138:139], v38 offset:4096
	s_waitcnt lgkmcnt(13)
	v_mfma_f32_16x16x32_bf16 v[172:175], v[128:131], v[164:167], v[172:175]
	ds_read_b64_tr_b16 v[140:141], v39 offset:0
	ds_read_b64_tr_b16 v[142:143], v39 offset:4096
	s_waitcnt lgkmcnt(14)
	s_cmp_eq_u32 s11, 0
	s_cbranch_scc1 .Lsc5_nopv1_5
	v_mfma_f32_16x16x32_bf16 v[172:175], v[132:135], v[168:171], v[172:175]

; #define SCAN_BAR() asm volatile("s_waitcnt lgkmcnt(0)\n\ts_barrier" ::: "memory")
; __device__ void scan_phase(LAS unsigned char* lds, const Params& p) {
;     ...
;         SCAN_LOAD(0, k4A, q4A, v4A, rvA, tlA); SCAN_LOAD(1, k4B, q4B, v4B, rvB, tlB); SCAN_LOAD(2, k4C, q4C, v4C, rvC, tlC); SCAN_LOAD(3, k4D, q4D, v4D, rvD, tlD);
;         SCAN_STAGE(0, k4A, q4A, v4A, rvA, tlA); SCAN_LOAD(4, k4A, q4A, v4A, rvA, tlA);
;         SCAN_BAR();
; #pragma unroll 1
;         for (int n0 = 0; n0 < 68; n0 += 4) {
;             SCAN_STAGE(1, k4B, q4B, v4B, rvB, tlB); SCAN_LOAD(min(n0 + 5, 67), k4B, q4B, v4B, rvB, tlB); SCAN_MAT(0, n0); SCAN_BAR();
;             SCAN_STAGE(0, k4C, q4C, v4C, rvC, tlC); SCAN_LOAD(min(n0 + 6, 67), k4C, q4C, v4C, rvC, tlC); SCAN_MAT(1, n0 + 1); SCAN_BAR();
;             SCAN_STAGE(1, k4D, q4D, v4D, rvD, tlD); SCAN_LOAD(min(n0 + 7, 67), k4D, q4D, v4D, rvD, tlD); SCAN_MAT(0, n0 + 2); SCAN_BAR();
;             SCAN_STAGE(0, k4A, q4A, v4A, rvA, tlA); SCAN_LOAD(min(n0 + 8, 67), k4A, q4A, v4A, rvA, tlA); SCAN_MAT(1, n0 + 3); SCAN_BAR();
.Lsc5_noy3_5:
	ds_write_b64 v84, v[160:161]
	ds_write_b64 v84, v[162:163] offset:1024
	s_waitcnt vmcnt(12)
	s_waitcnt lgkmcnt(0)
	s_barrier
	s_add_u32 s34, s34, 6
	s_cmp_lt_u32 s34, 66
	s_cbranch_scc1 .Lsc5_loop
	ds_read_b32 v50, v79 offset:512
	ds_read_b32 v51, v79 offset:576
	ds_read_b64_tr_b16 v[128:129], v72 offset:0
	ds_read_b64_tr_b16 v[130:131], v72 offset:1152
	ds_read_b64_tr_b16 v[132:133], v72 offset:2304
	ds_read_b64_tr_b16 v[134:135], v72 offset:3456
	ds_read_b64_tr_b16 v[112:113], v82 offset:0
	ds_read_b64_tr_b16 v[114:115], v82 offset:288
	ds_read_b64_tr_b16 v[116:117], v82 offset:2304
	ds_read_b64_tr_b16 v[118:119], v82 offset:2592
	ds_read_b64_tr_b16 v[120:121], v82 offset:4608
	ds_read_b64_tr_b16 v[122:123], v82 offset:4896
	ds_read_b64_tr_b16 v[124:125], v82 offset:6912
	ds_read_b64_tr_b16 v[126:127], v82 offset:7200
	s_add_u32 s3, s34, 3
	s_min_u32 s3, s3, 67
	s_cmp_lt_u32 s3, 4
	s_cselect_b32 s4, s16, s17
	s_mul_i32 s5, s3, s15
	s_add_i32 s4, s4, s5
	s_lshl_b32 s5, s4, 14
	s_lshl_b32 s4, s4, 11
	s_add_u32 s40, s18, s5
	s_addc_u32 s41, s19, 0
	s_add_u32 s42, s20, s5
	s_addc_u32 s43, s21, 0
	s_add_u32 m0, s12, 0
	s_nop 0
	global_load_lds_dwordx4 v53, s[40:41]
	s_add_u32 m0, s12, 8192
	s_nop 0
	global_load_lds_dwordx4 v54, s[40:41]
	s_add_u32 m0, s12, 16384
	s_nop 0
	global_load_lds_dwordx4 v53, s[42:43]
	s_add_u32 m0, s12, 24576
	s_nop 0
	global_load_lds_dwordx4 v54, s[42:43]
	s_add_u32 s3, s34, 4
	s_min_u32 s3, s3, 67
	s_cmp_lt_u32 s3, 4
	s_cselect_b32 s4, s16, s17
	s_mul_i32 s5, s3, s15
	s_add_i32 s4, s4, s5
	s_lshl_b32 s5, s4, 14
	s_lshl_b32 s4, s4, 11
	s_add_u32 s44, s22, s5
	s_addc_u32 s45, s23, 0
	s_add_u32 s46, s24, s4
	s_addc_u32 s47, s25, 0
	s_add_u32 s50, s26, s4
	s_addc_u32 s51, s27, 0
	global_load_dwordx2 v[6:7], v55, s[44:45]
	global_load_dword v8, v56, s[46:47]
	global_load_dword v9, v56, s[50:51]
	s_waitcnt lgkmcnt(8)
	v_mfma_f32_16x16x32_bf16 v[42:45], v[128:131], v[136:139], v[42:45]
	ds_read_b128 v[164:167], v86
	ds_read_b128 v[168:171], v86 offset:1024
	v_mfma_f32_16x16x32_bf16 v[46:49], v[128:131], v[140:143], v[46:49]
	ds_read_b128 v[200:203], v18
	ds_read_b128 v[204:207], v19
	v_mfma_f32_16x16x32_bf16 v[42:45], v[132:135], v[144:147], v[42:45]
	ds_read_b128 v[208:211], v20
	ds_read_b128 v[212:215], v21
	v_mfma_f32_16x16x32_bf16 v[46:49], v[132:135], v[148:151], v[46:49]
	s_waitcnt lgkmcnt(12)
	v_mfma_f32_16x16x32_bf16 v[172:175], v[112:115], v[96:99], 0
	s_waitcnt vmcnt(16)
	ds_write_b64 v65, v[10:11]
	v_add_f32_e32 v92, v12, v52
	v_mul_f32_e32 v92, 0x3fb8aa3b, v92
	v_exp_f32_e32 v92, v92
	v_mov_b32_e32 v52, v13
	ds_write_b32 v78, v92 offset:1024
	s_waitcnt lgkmcnt(12)
	v_mfma_f32_16x16x32_bf16 v[172:175], v[116:119], v[100:103], v[172:175]
	ds_read_b128 v[216:219], v30
	ds_read_b128 v[220:223], v31
	s_waitcnt lgkmcnt(12)
	v_mfma_f32_16x16x32_bf16 v[172:175], v[120:123], v[104:107], v[172:175]
	ds_read_b128 v[224:227], v32
	ds_read_b128 v[228:231], v33
	s_waitcnt lgkmcnt(12)
	v_mfma_f32_16x16x32_bf16 v[172:175], v[124:127], v[108:111], v[172:175]
	ds_read_b64_tr_b16 v[188:189], v40 offset:0
	ds_read_b64_tr_b16 v[190:191], v40 offset:4096
	s_waitcnt lgkmcnt(13)
	v_mfma_f32_16x16x32_bf16 v[172:175], v[128:131], v[164:167], v[172:175]
	ds_read_b64_tr_b16 v[192:193], v41 offset:0
	ds_read_b64_tr_b16 v[194:195], v41 offset:4096
	s_waitcnt lgkmcnt(14)
	s_cmp_eq_u32 s11, 0
	s_cbranch_scc1 .Lsc5_nopv1_t0
	v_mfma_f32_16x16x32_bf16 v[172:175], v[132:135], v[168:171], v[172:175]

.Lsc5_noy3_t0:
	ds_write_b64 v85, v[160:161]
	ds_write_b64 v85, v[162:163] offset:1024
	s_waitcnt vmcnt(12)
	s_waitcnt lgkmcnt(0)
	s_barrier
	ds_read_b64_tr_b16 v[128:129], v73 offset:0
	ds_read_b64_tr_b16 v[130:131], v73 offset:1152
	ds_read_b64_tr_b16 v[132:133], v73 offset:2304
	ds_read_b64_tr_b16 v[134:135], v73 offset:3456
	ds_read_b64_tr_b16 v[112:113], v83 offset:0
	ds_read_b64_tr_b16 v[114:115], v83 offset:288
	ds_read_b64_tr_b16 v[116:117], v83 offset:2304
	ds_read_b64_tr_b16 v[118:119], v83 offset:2592
	ds_read_b64_tr_b16 v[120:121], v83 offset:4608
	ds_read_b64_tr_b16 v[122:123], v83 offset:4896
	ds_read_b64_tr_b16 v[124:125], v83 offset:6912
	ds_read_b64_tr_b16 v[126:127], v83 offset:7200
	s_add_u32 s3, s34, 4
	s_min_u32 s3, s3, 67
	s_cmp_lt_u32 s3, 4
	s_cselect_b32 s4, s16, s17
	s_mul_i32 s5, s3, s15
	s_add_i32 s4, s4, s5
	s_lshl_b32 s5, s4, 14
	s_lshl_b32 s4, s4, 11
	s_add_u32 s40, s18, s5
	s_addc_u32 s41, s19, 0
	s_add_u32 s42, s20, s5
	s_addc_u32 s43, s21, 0
	s_add_u32 m0, s12, 32768
	s_nop 0
	global_load_lds_dwordx4 v53, s[40:41]
	s_add_u32 m0, s12, 40960
	s_nop 0
	global_load_lds_dwordx4 v54, s[40:41]
	s_add_u32 m0, s12, 49152
	s_nop 0
	global_load_lds_dwordx4 v53, s[42:43]
	s_add_u32 m0, s12, 57344
	s_nop 0
	global_load_lds_dwordx4 v54, s[42:43]
	s_add_u32 s3, s34, 5
	s_min_u32 s3, s3, 67
	s_cmp_lt_u32 s3, 4
	s_cselect_b32 s4, s16, s17
	s_mul_i32 s5, s3, s15
	s_add_i32 s4, s4, s5
	s_lshl_b32 s5, s4, 14
	s_lshl_b32 s4, s4, 11
	s_add_u32 s44, s22, s5
	s_addc_u32 s45, s23, 0
	s_add_u32 s46, s24, s4
	s_addc_u32 s47, s25, 0
	s_add_u32 s50, s26, s4
	s_addc_u32 s51, s27, 0
	global_load_dwordx2 v[10:11], v55, s[44:45]
	global_load_dword v12, v56, s[46:47]
	global_load_dword v13, v56, s[50:51]
	s_waitcnt lgkmcnt(8)
	v_mfma_f32_16x16x32_bf16 v[42:45], v[128:131], v[188:191], v[42:45]
	ds_read_b128 v[164:167], v87
	ds_read_b128 v[168:171], v87 offset:1024
	v_mfma_f32_16x16x32_bf16 v[46:49], v[128:131], v[192:195], v[46:49]
	v_mfma_f32_16x16x32_bf16 v[42:45], v[132:135], v[196:199], v[42:45]
	v_mfma_f32_16x16x32_bf16 v[46:49], v[132:135], v[248:251], v[46:49]
	s_waitcnt lgkmcnt(8)
	v_mfma_f32_16x16x32_bf16 v[172:175], v[112:115], v[200:203], 0
	s_waitcnt vmcnt(16)
	ds_write_b64 v63, v[2:3]
	v_add_f32_e32 v92, v4, v52
	v_mul_f32_e32 v92, 0x3fb8aa3b, v92
	v_exp_f32_e32 v92, v92
	v_mov_b32_e32 v52, v5
	ds_write_b32 v78, v92 offset:0
	s_waitcnt lgkmcnt(8)
	v_mfma_f32_16x16x32_bf16 v[172:175], v[116:119], v[204:207], v[172:175]
	s_waitcnt lgkmcnt(6)
	v_mfma_f32_16x16x32_bf16 v[172:175], v[120:123], v[208:211], v[172:175]
	s_waitcnt lgkmcnt(4)
	v_mfma_f32_16x16x32_bf16 v[172:175], v[124:127], v[212:215], v[172:175]
	s_waitcnt lgkmcnt(3)
	v_mfma_f32_16x16x32_bf16 v[172:175], v[128:131], v[164:167], v[172:175]
	s_waitcnt lgkmcnt(2)
	s_cmp_eq_u32 s11, 0
	s_cbranch_scc1 .Lsc5_nopv1_t1
	v_mfma_f32_16x16x32_bf16 v[172:175], v[132:135], v[168:171], v[172:175]
